# scan loader: kd/r ds_write_b128 issued at the end of the iteration instead of right after the chunk barrier (away from the compute waves' read burst)
# baseline (speedup 1.0000x reference)
.Lscan_ld_steady_a:
	v_add_u32_e32 v38, s72, v91
	v_add_u32_e32 v95, v38, v92
	s_waitcnt vmcnt(19)
	v_lshlrev_b32_e32 v4, 16, v56
	v_and_b32_e32 v5, 0xffff0000, v56
	v_lshlrev_b32_e32 v6, 16, v57
	v_and_b32_e32 v7, 0xffff0000, v57
	v_mov_b32_e32 v12, v95
	s_waitcnt vmcnt(18)
	s_waitcnt vmcnt(17)
	s_waitcnt vmcnt(16)
	v_lshlrev_b32_e32 v8, 16, v58
	v_and_b32_e32 v9, 0xffff0000, v58
	v_lshlrev_b32_e32 v10, 16, v59
	v_and_b32_e32 v11, 0xffff0000, v59
	s_and_saveexec_b64 s[26:27], s[44:45]
	s_cbranch_execz .LBB0_1109
	v_lshlrev_b32_e32 v42, 2, v93
	v_lshlrev_b32_e32 v43, 2, v94
	v_add3_u32 v42, s72, v42, v43
	s_waitcnt vmcnt(15)
	v_lshlrev_b32_e32 v38, 16, v74
	v_and_b32_e32 v39, 0xffff0000, v74
	v_add_u32_e32 v42, 0x5000, v42
	v_lshlrev_b32_e32 v40, 16, v75
	v_and_b32_e32 v41, 0xffff0000, v75
	ds_write2_b32 v42, v38, v39 offset1:16
	ds_write2_b32 v42, v40, v41 offset0:32 offset1:48
	s_or_b64 exec, exec, s[26:27]
	s_cmpk_gt_u32 s49, 0x10b
	s_cbranch_scc0 .LBB0_1110

.LBB0_1162:
	ds_write_b128 v12, v[4:7] offset:4096
	ds_write_b128 v12, v[8:11] offset:16384
	s_waitcnt vmcnt(17)
	s_waitcnt lgkmcnt(0)
	s_barrier
	s_cmpk_lt_u32 s49, 6
	s_cbranch_scc1 .Lscan_ld_drain_b
	s_cmpk_lt_u32 s49, 0x109
	s_cbranch_scc1 .Lscan_ld_steady_b

.Lscan_ld_steady_b:
	s_cmpk_lt_u32 s49, 0x10e
	s_cselect_b64 s[60:61], -1, 0
	s_cmpk_gt_u32 s49, 0x10d
	s_cbranch_scc1 .LBB0_1167
	s_bitcmp1_b32 s49, 0
	s_cselect_b32 s2, 0x5400, 0
	s_add_i32 s33, s2, 0
	v_add3_u32 v42, s33, v91, v92
	s_waitcnt vmcnt(19)
	v_lshlrev_b32_e32 v4, 16, v76
	v_and_b32_e32 v5, 0xffff0000, v76
	v_lshlrev_b32_e32 v6, 16, v77
	v_and_b32_e32 v7, 0xffff0000, v77
	v_mov_b32_e32 v12, v42
	s_waitcnt vmcnt(18)
	s_waitcnt vmcnt(17)
	s_waitcnt vmcnt(16)
	v_lshlrev_b32_e32 v8, 16, v78
	v_and_b32_e32 v9, 0xffff0000, v78
	v_lshlrev_b32_e32 v10, 16, v79
	v_and_b32_e32 v11, 0xffff0000, v79
	s_and_saveexec_b64 s[26:27], s[44:45]
	s_cbranch_execz .LBB0_1165
	v_lshlrev_b32_e32 v42, 2, v93
	v_lshlrev_b32_e32 v43, 2, v94
	v_add3_u32 v42, s33, v42, v43
	s_waitcnt vmcnt(15)
	v_lshlrev_b32_e32 v38, 16, v80
	v_and_b32_e32 v39, 0xffff0000, v80
	v_add_u32_e32 v42, 0x5000, v42
	v_lshlrev_b32_e32 v40, 16, v81
	v_and_b32_e32 v41, 0xffff0000, v81
	ds_write2_b32 v42, v38, v39 offset1:16
	ds_write2_b32 v42, v40, v41 offset0:32 offset1:48

.LBB0_1209:
	s_cmpk_gt_u32 s49, 0x10d
	s_cbranch_scc1 .Ldefer_skip_b
	ds_write_b128 v12, v[4:7] offset:4096
	ds_write_b128 v12, v[8:11] offset:16384

.Lscan_ld_steady_c:
	s_cbranch_vccnz .LBB0_1105
	s_cmpk_eq_i32 s49, 0x10d
	s_cbranch_scc1 .LBB0_1226
	s_waitcnt vmcnt(19)
	v_lshlrev_b32_e32 v4, 16, v82
	v_and_b32_e32 v5, 0xffff0000, v82
	v_lshlrev_b32_e32 v6, 16, v83
	v_and_b32_e32 v7, 0xffff0000, v83
	v_mov_b32_e32 v12, v95
	s_waitcnt vmcnt(18)
	s_waitcnt vmcnt(17)
	s_waitcnt vmcnt(16)
	v_lshlrev_b32_e32 v8, 16, v84
	v_and_b32_e32 v9, 0xffff0000, v84
	v_lshlrev_b32_e32 v10, 16, v85
	v_and_b32_e32 v11, 0xffff0000, v85
	s_and_saveexec_b64 s[26:27], s[44:45]
	s_cbranch_execz .LBB0_1225
	v_lshlrev_b32_e32 v42, 2, v93
	v_lshlrev_b32_e32 v43, 2, v94
	v_add3_u32 v42, s72, v42, v43
	s_waitcnt vmcnt(15)
	v_lshlrev_b32_e32 v38, 16, v86
	v_and_b32_e32 v39, 0xffff0000, v86
	v_add_u32_e32 v42, 0x5000, v42
	v_lshlrev_b32_e32 v40, 16, v87
	v_and_b32_e32 v41, 0xffff0000, v87
	ds_write2_b32 v42, v38, v39 offset1:16
	ds_write2_b32 v42, v40, v41 offset0:32 offset1:48

.LBB0_1266:
	s_cmpk_eq_i32 s49, 0x10d
	s_cbranch_scc1 .Ldefer_skip_c
	ds_write_b128 v12, v[4:7] offset:4096
	ds_write_b128 v12, v[8:11] offset:16384
